# one static s_setprio 1 for waves 4-7 at kernel entry (all per-phase toggles already removed)
# baseline (speedup 1.0000x reference)
; #define LAS __attribute__((address_space(3)))
; DI int lane_id_() { unsigned m = ~0u; asm volatile("" : "+s"(m)); return (int)__builtin_amdgcn_mbcnt_hi(m, __builtin_amdgcn_mbcnt_lo(m, 0u)); }
; __global__ void __launch_bounds__(512, 2) mega(Params p) {
;     extern __shared__ __attribute__((aligned(16))) unsigned char lds_raw[];
;     LAS unsigned char* lds = (LAS unsigned char*)lds_raw;
;     cg::grid_group grid = cg::this_grid();
;     const int wv = __builtin_amdgcn_readfirstlane((int)threadIdx.x >> 6);
;     const int G = GRID, bid = blockIdx.x;
;     ...
;     volatile LAS unsigned* MISC = (volatile LAS unsigned*)(lds + LDS_BYTES - 256);
;     if (wv == 0 && lane_id_() < 16) MISC[lane_id_()] = 0u;
;     __syncthreads();
_Z4mega6Params:
	s_load_dwordx2 s[60:61], s[0:1], 0x90
	v_and_b32_e32 v1, 0x3ff, v0
	s_mov_b32 s85, s2
	v_readfirstlane_b32 s33, v1
	s_nop 3
	s_cmp_ge_u32 s33, 0x100
	s_cbranch_scc0 .Lprio_skip
	s_setprio 1
.Lprio_skip:
	s_cmp_lt_u32 s33, 64
	s_cselect_b64 s[2:3], -1, 0
	s_cmp_gt_u32 s33, 63
	s_cbranch_scc1 .LBB0_4
	s_mov_b32 s4, -1
	s_mov_b32 s6, -1
	v_mbcnt_lo_u32_b32 v2, s4, 0
	v_mbcnt_hi_u32_b32 v2, s4, v2
	v_cmp_gt_i32_e32 vcc, 16, v2
	s_and_saveexec_b64 s[4:5], vcc
	s_cbranch_execz .LBB0_3
	v_mov_b32_e32 v2, 0
	v_mbcnt_lo_u32_b32 v3, s6, 0
	v_mbcnt_hi_u32_b32 v3, s6, v3
	v_lshl_add_u32 v3, v3, 2, 0
	v_add_u32_e32 v3, 0x25f00, v3
	ds_write_b32 v3, v2
